# ph4 gates epilogue: second-half param loads issued early into dead acc regs, mid-epilogue vmcnt(0) drains replaced by counted waits
# speedup vs baseline: 1.0277x; 1.0082x over previous
.LBB0_1002:
	v_mov_b32_e32 v66, v179
	s_and_b32 s2, s1, 1
	v_ashrrev_i32_e32 v67, 2, v66
	v_and_b32_e32 v67, 0xffffffc0, v67
	v_lshl_add_u32 v67, s0, 8, v67
	v_and_or_b32 v222, v66, 15, v67
	s_lshl_b32 s0, s1, 6
	v_lshrrev_b32_e32 v66, 1, v66
	s_and_b32 s0, s0, 0xffffff80
	v_and_b32_e32 v66, 0x78, v66
	v_or_b32_e32 v162, s0, v66
	s_mul_i32 s0, s2, 0x5000000
	v_ashrrev_i32_e32 v163, 31, v162
	s_add_u32 s0, s73, s0
	s_addc_u32 s1, s21, 0
	v_lshlrev_b64 v[170:171], 2, v[162:163]
	s_lshl_b32 s2, s2, 12
	v_lshl_add_u64 v[204:205], s[0:1], 0, v[170:171]
	s_add_u32 s0, s34, s2
	s_addc_u32 s1, s35, 0
	v_lshl_add_u64 v[206:207], s[0:1], 0, v[170:171]
	v_lshl_add_u64 v[66:67], v[162:163], 1, s[42:43]
	global_load_dwordx4 v[162:165], v[206:207], off
	s_add_u32 s0, s30, s2
	s_addc_u32 s1, s31, 0
	v_lshl_add_u64 v[208:209], s[0:1], 0, v[170:171]
	s_add_u32 s0, s16, s2
	v_ashrrev_i32_e32 v223, 31, v222
	s_addc_u32 s1, s17, 0
	v_lshlrev_b64 v[70:71], 11, v[222:223]
	v_lshl_add_u64 v[210:211], s[0:1], 0, v[170:171]
	v_lshl_add_u64 v[70:71], v[66:67], 0, v[70:71]
	global_load_dwordx4 v[170:173], v[210:211], off
	global_load_dwordx4 v[158:161], v[70:71], off
	global_load_dwordx4 v[166:169], v[208:209], off
	v_add_u32_e32 v214, 0x80, v222
	v_ashrrev_i32_e32 v215, 31, v214
	v_lshlrev_b64 v[68:69], 11, v[214:215]
	v_lshl_add_u64 v[68:69], v[66:67], 0, v[68:69]
	global_load_dwordx4 v[86:89], v[68:69], off
	v_or_b32_e32 v220, 16, v222
	v_add_u32_e32 v212, 0x90, v222
	v_ashrrev_i32_e32 v221, 31, v220
	v_ashrrev_i32_e32 v213, 31, v212
	v_lshlrev_b64 v[70:71], 11, v[220:221]
	v_or_b32_e32 v218, 32, v222
	v_lshlrev_b64 v[68:69], 11, v[212:213]
	v_lshl_add_u64 v[70:71], v[66:67], 0, v[70:71]
	v_ashrrev_i32_e32 v219, 31, v218
	v_lshl_add_u64 v[68:69], v[66:67], 0, v[68:69]
	global_load_dwordx4 v[122:125], v[70:71], off
	global_load_dwordx4 v[74:77], v[68:69], off
	v_lshlrev_b64 v[70:71], 11, v[218:219]
	v_or_b32_e32 v216, 48, v222
	v_add_u32_e32 v202, 0xa0, v222
	v_lshl_add_u64 v[70:71], v[66:67], 0, v[70:71]
	v_ashrrev_i32_e32 v217, 31, v216
	v_ashrrev_i32_e32 v203, 31, v202
	global_load_dwordx4 v[110:113], v[70:71], off
	v_lshlrev_b64 v[70:71], 11, v[216:217]
	v_lshlrev_b64 v[68:69], 11, v[202:203]
	v_add_u32_e32 v200, 0xb0, v222
	v_lshl_add_u64 v[70:71], v[66:67], 0, v[70:71]
	v_lshl_add_u64 v[68:69], v[66:67], 0, v[68:69]
	v_ashrrev_i32_e32 v201, 31, v200
	global_load_dwordx4 v[98:101], v[70:71], off
	s_waitcnt vmcnt(0)
	v_add_f32_e32 v154, v154, v162
	v_mul_f32_e32 v154, 0xbfb8aa3b, v154
	v_exp_f32_e32 v154, v154
	global_load_dwordx4 v[70:73], v[68:69], off
	v_lshlrev_b64 v[68:69], 11, v[200:201]
	v_lshl_add_u64 v[66:67], v[66:67], 0, v[68:69]
	v_add_f32_e32 v154, 1.0, v154
	v_rcp_f32_e64 v154, -v154
	global_load_dwordx4 v[66:69], v[66:67], off
	v_mul_f32_e32 v154, v170, v154
	v_lshlrev_b32_e32 v227, 16, v158
	v_and_b32_e32 v228, 0xffff0000, v158
	v_lshlrev_b32_e32 v226, 16, v159
	v_and_b32_e32 v158, 0xffff0000, v159
	v_add_f32_e32 v159, v154, v154
	v_mul_f32_e32 v159, 0x3fb8aa3b, v159
	v_add_f32_e32 v150, v150, v166
	v_exp_f32_e32 v159, v159
	v_mul_f32_e32 v150, 0xbfb8aa3b, v150
	v_exp_f32_e32 v150, v150
	v_add_f32_e32 v151, v151, v167
	v_sub_f32_e32 v159, 1.0, v159
	v_max_f32_e32 v159, 0x1e3ce508, v159
	v_add_f32_e32 v150, 1.0, v150
	v_mul_f32_e32 v229, v150, v159
	v_mul_f32_e32 v150, v150, v229
	v_rsq_f32_e32 v150, v150
	v_mul_f32_e32 v151, 0xbfb8aa3b, v151
	v_exp_f32_e32 v151, v151
	v_add_f32_e32 v152, v152, v168
	v_mul_f32_e32 v150, v159, v150
	v_mul_f32_e32 v150, v150, v227
	v_cvt_pk_bf16_f32 v150, v154, v150
	v_add_f32_e32 v154, v155, v163
	v_mul_f32_e32 v154, 0xbfb8aa3b, v154
	v_exp_f32_e32 v154, v154
	v_add_f32_e32 v151, 1.0, v151
	v_mul_f32_e32 v152, 0xbfb8aa3b, v152
	v_exp_f32_e32 v152, v152
	v_add_f32_e32 v154, 1.0, v154
	v_rcp_f32_e64 v154, -v154
	v_add_f32_e32 v153, v153, v169
	v_add_f32_e32 v152, 1.0, v152
	v_mul_f32_e32 v153, 0xbfb8aa3b, v153
	v_mul_f32_e32 v154, v171, v154
	v_add_f32_e32 v155, v154, v154
	v_mul_f32_e32 v155, 0x3fb8aa3b, v155
	v_exp_f32_e32 v155, v155
	v_exp_f32_e32 v153, v153
	v_sub_f32_e32 v155, 1.0, v155
	v_max_f32_e32 v155, 0x1e3ce508, v155
	v_mul_f32_e32 v159, v151, v155
	v_mul_f32_e32 v151, v151, v159
	v_rsq_f32_e32 v151, v151
	v_add_f32_e32 v153, 1.0, v153
	v_mul_f32_e32 v151, v155, v151
	v_mul_f32_e32 v151, v151, v228
	v_cvt_pk_bf16_f32 v151, v154, v151
	v_add_f32_e32 v154, v156, v164
	v_mul_f32_e32 v154, 0xbfb8aa3b, v154
	v_exp_f32_e32 v154, v154
	s_nop 0
	v_add_f32_e32 v154, 1.0, v154
	v_rcp_f32_e64 v154, -v154
	s_nop 0
	v_mul_f32_e32 v154, v172, v154
	v_add_f32_e32 v155, v154, v154
	v_mul_f32_e32 v155, 0x3fb8aa3b, v155
	v_exp_f32_e32 v155, v155
	s_nop 0
	v_sub_f32_e32 v155, 1.0, v155
	v_max_f32_e32 v155, 0x1e3ce508, v155
	v_mul_f32_e32 v156, v152, v155
	v_mul_f32_e32 v152, v152, v156
	v_rsq_f32_e32 v152, v152
	s_nop 0
	v_mul_f32_e32 v152, v155, v152
	v_mul_f32_e32 v152, v152, v226
	v_cvt_pk_bf16_f32 v152, v154, v152
	v_add_f32_e32 v154, v157, v165
	v_mul_f32_e32 v154, 0xbfb8aa3b, v154
	v_exp_f32_e32 v154, v154
	s_nop 0
	v_add_f32_e32 v154, 1.0, v154
	v_rcp_f32_e64 v154, -v154
	s_nop 0
	v_mul_f32_e32 v154, v173, v154
	v_add_f32_e32 v155, v154, v154
	v_mul_f32_e32 v155, 0x3fb8aa3b, v155
	v_exp_f32_e32 v155, v155
	s_nop 0
	v_sub_f32_e32 v155, 1.0, v155
	v_max_f32_e32 v155, 0x1e3ce508, v155
	v_mul_f32_e32 v156, v153, v155
	v_mul_f32_e32 v153, v153, v156
	v_rsq_f32_e32 v153, v153
	s_nop 0
	v_mul_f32_e32 v153, v155, v153
	v_mul_f32_e32 v153, v153, v158
	v_cvt_pk_bf16_f32 v153, v154, v153
	v_lshlrev_b64 v[154:155], 12, v[222:223]
	v_lshl_add_u64 v[154:155], v[204:205], 0, v[154:155]
	global_store_dwordx4 v[154:155], v[150:153], off
	v_add_f32_e32 v146, v146, v162
	v_mul_f32_e32 v146, 0xbfb8aa3b, v146
	v_exp_f32_e32 v146, v146
	v_add_f32_e32 v142, v142, v166
	v_mul_f32_e32 v142, 0xbfb8aa3b, v142
	v_exp_f32_e32 v142, v142
	v_add_f32_e32 v146, 1.0, v146
	v_rcp_f32_e64 v146, -v146
	v_add_f32_e32 v147, v147, v163
	v_mul_f32_e32 v147, 0xbfb8aa3b, v147
	v_add_f32_e32 v142, 1.0, v142
	v_mul_f32_e32 v146, v170, v146
	v_add_f32_e32 v152, v146, v146
	v_mul_f32_e32 v152, 0x3fb8aa3b, v152
	v_exp_f32_e32 v152, v152
	v_exp_f32_e32 v147, v147
	v_lshlrev_b32_e32 v150, 16, v122
	v_add_f32_e32 v143, v143, v167
	v_sub_f32_e32 v152, 1.0, v152
	v_max_f32_e32 v152, 0x1e3ce508, v152
	v_mul_f32_e32 v153, v142, v152
	v_mul_f32_e32 v142, v142, v153
	v_rsq_f32_e32 v142, v142
	v_add_f32_e32 v147, 1.0, v147
	v_rcp_f32_e64 v147, -v147
	v_mul_f32_e32 v143, 0xbfb8aa3b, v143
	v_mul_f32_e32 v142, v152, v142
	v_mul_f32_e32 v142, v142, v150
	v_cvt_pk_bf16_f32 v142, v146, v142
	v_mul_f32_e32 v146, v171, v147
	v_add_f32_e32 v147, v146, v146
	v_mul_f32_e32 v147, 0x3fb8aa3b, v147
	v_exp_f32_e32 v147, v147
	v_exp_f32_e32 v143, v143
	v_add_f32_e32 v148, v148, v164
	v_mul_f32_e32 v148, 0xbfb8aa3b, v148
	v_sub_f32_e32 v147, 1.0, v147
	v_max_f32_e32 v147, 0x1e3ce508, v147
	v_add_f32_e32 v143, 1.0, v143
	v_exp_f32_e32 v148, v148
	v_mul_f32_e32 v150, v143, v147
	v_mul_f32_e32 v143, v143, v150
	v_rsq_f32_e32 v143, v143
	v_add_f32_e32 v148, 1.0, v148
	v_rcp_f32_e64 v148, -v148
	v_and_b32_e32 v122, 0xffff0000, v122
	v_mul_f32_e32 v143, v147, v143
	v_mul_f32_e32 v122, v143, v122
	v_cvt_pk_bf16_f32 v143, v146, v122
	v_add_f32_e32 v146, v149, v165
	v_mul_f32_e32 v146, 0xbfb8aa3b, v146
	v_mul_f32_e32 v148, v172, v148
	v_exp_f32_e32 v146, v146
	v_add_f32_e32 v150, v148, v148
	v_mul_f32_e32 v150, 0x3fb8aa3b, v150
	v_add_f32_e32 v144, v144, v168
	v_exp_f32_e32 v150, v150
	v_mul_f32_e32 v144, 0xbfb8aa3b, v144
	v_exp_f32_e32 v144, v144
	v_add_f32_e32 v146, 1.0, v146
	v_rcp_f32_e64 v146, -v146
	v_sub_f32_e32 v122, 1.0, v150
	v_max_f32_e32 v122, 0x1e3ce508, v122
	v_add_f32_e32 v144, 1.0, v144
	v_mul_f32_e32 v147, v144, v122
	v_mul_f32_e32 v146, v173, v146
	v_mul_f32_e32 v144, v144, v147
	v_add_f32_e32 v147, v146, v146
	v_mul_f32_e32 v147, 0x3fb8aa3b, v147
	v_add_f32_e32 v145, v145, v169
	v_exp_f32_e32 v147, v147
	v_mul_f32_e32 v145, 0xbfb8aa3b, v145
	v_exp_f32_e32 v145, v145
	v_rsq_f32_e32 v144, v144
	v_sub_f32_e32 v147, 1.0, v147
	v_max_f32_e32 v147, 0x1e3ce508, v147
	v_add_f32_e32 v145, 1.0, v145
	v_mul_f32_e32 v149, v145, v147
	v_mul_f32_e32 v145, v145, v149
	v_rsq_f32_e32 v145, v145
	v_lshlrev_b32_e32 v151, 16, v123
	v_mul_f32_e32 v122, v122, v144
	v_mul_f32_e32 v122, v122, v151
	v_and_b32_e32 v123, 0xffff0000, v123
	v_cvt_pk_bf16_f32 v144, v148, v122
	v_mul_f32_e32 v122, v147, v145
	v_mul_f32_e32 v122, v122, v123
	v_cvt_pk_bf16_f32 v145, v146, v122
	v_lshlrev_b64 v[122:123], 12, v[220:221]
	v_lshl_add_u64 v[122:123], v[204:205], 0, v[122:123]
	global_store_dwordx4 v[122:123], v[142:145], off
	global_load_dwordx4 v[146:149], v[206:207], off offset:16
	global_load_dwordx4 v[150:153], v[208:209], off offset:16
	global_load_dwordx4 v[156:159], v[210:211], off offset:16
	v_add_f32_e32 v138, v138, v162
	v_mul_f32_e32 v138, 0xbfb8aa3b, v138
	v_exp_f32_e32 v138, v138
	v_add_f32_e32 v134, v134, v166
	v_mul_f32_e32 v134, 0xbfb8aa3b, v134
	v_exp_f32_e32 v134, v134
	v_add_f32_e32 v138, 1.0, v138
	v_rcp_f32_e64 v138, -v138
	v_add_f32_e32 v139, v139, v163
	v_mul_f32_e32 v139, 0xbfb8aa3b, v139
	v_add_f32_e32 v134, 1.0, v134
	v_mul_f32_e32 v138, v170, v138
	v_add_f32_e32 v144, v138, v138
	v_mul_f32_e32 v144, 0x3fb8aa3b, v144
	v_exp_f32_e32 v144, v144
	v_exp_f32_e32 v139, v139
	v_lshlrev_b32_e32 v142, 16, v110
	v_add_f32_e32 v135, v135, v167
	v_sub_f32_e32 v144, 1.0, v144
	v_max_f32_e32 v144, 0x1e3ce508, v144
	v_mul_f32_e32 v145, v134, v144
	v_mul_f32_e32 v134, v134, v145
	v_rsq_f32_e32 v134, v134
	v_add_f32_e32 v139, 1.0, v139
	v_rcp_f32_e64 v139, -v139
	v_mul_f32_e32 v135, 0xbfb8aa3b, v135
	v_mul_f32_e32 v134, v144, v134
	v_mul_f32_e32 v134, v134, v142
	v_cvt_pk_bf16_f32 v134, v138, v134
	v_mul_f32_e32 v138, v171, v139
	v_add_f32_e32 v139, v138, v138
	v_mul_f32_e32 v139, 0x3fb8aa3b, v139
	v_exp_f32_e32 v139, v139
	v_exp_f32_e32 v135, v135
	v_add_f32_e32 v140, v140, v164
	v_mul_f32_e32 v140, 0xbfb8aa3b, v140
	v_sub_f32_e32 v139, 1.0, v139
	v_max_f32_e32 v139, 0x1e3ce508, v139
	v_add_f32_e32 v135, 1.0, v135
	v_exp_f32_e32 v140, v140
	v_mul_f32_e32 v142, v135, v139
	v_mul_f32_e32 v135, v135, v142
	v_rsq_f32_e32 v135, v135
	v_add_f32_e32 v140, 1.0, v140
	v_rcp_f32_e64 v140, -v140
	v_and_b32_e32 v110, 0xffff0000, v110
	v_mul_f32_e32 v135, v139, v135
	v_mul_f32_e32 v110, v135, v110
	v_cvt_pk_bf16_f32 v135, v138, v110
	v_add_f32_e32 v138, v141, v165
	v_mul_f32_e32 v138, 0xbfb8aa3b, v138
	v_mul_f32_e32 v140, v172, v140
	v_exp_f32_e32 v138, v138
	v_add_f32_e32 v142, v140, v140
	v_mul_f32_e32 v142, 0x3fb8aa3b, v142
	v_add_f32_e32 v136, v136, v168
	v_exp_f32_e32 v142, v142
	v_mul_f32_e32 v136, 0xbfb8aa3b, v136
	v_exp_f32_e32 v136, v136
	v_add_f32_e32 v138, 1.0, v138
	v_rcp_f32_e64 v138, -v138
	v_sub_f32_e32 v110, 1.0, v142
	v_max_f32_e32 v110, 0x1e3ce508, v110
	v_add_f32_e32 v136, 1.0, v136
	v_mul_f32_e32 v139, v136, v110
	v_mul_f32_e32 v138, v173, v138
	v_mul_f32_e32 v136, v136, v139
	v_add_f32_e32 v139, v138, v138
	v_mul_f32_e32 v139, 0x3fb8aa3b, v139
	v_add_f32_e32 v137, v137, v169
	v_exp_f32_e32 v139, v139
	v_mul_f32_e32 v137, 0xbfb8aa3b, v137
	v_exp_f32_e32 v137, v137
	v_rsq_f32_e32 v136, v136
	v_sub_f32_e32 v139, 1.0, v139
	v_max_f32_e32 v139, 0x1e3ce508, v139
	v_add_f32_e32 v137, 1.0, v137
	v_mul_f32_e32 v141, v137, v139
	v_mul_f32_e32 v137, v137, v141
	v_rsq_f32_e32 v137, v137
	v_lshlrev_b32_e32 v143, 16, v111
	v_mul_f32_e32 v110, v110, v136
	v_mul_f32_e32 v110, v110, v143
	v_and_b32_e32 v111, 0xffff0000, v111
	v_cvt_pk_bf16_f32 v136, v140, v110
	v_mul_f32_e32 v110, v139, v137
	v_mul_f32_e32 v110, v110, v111
	v_cvt_pk_bf16_f32 v137, v138, v110
	v_lshlrev_b64 v[110:111], 12, v[218:219]
	v_lshl_add_u64 v[110:111], v[204:205], 0, v[110:111]
	global_store_dwordx4 v[110:111], v[134:137], off
	v_add_f32_e32 v130, v130, v162
	v_mul_f32_e32 v130, 0xbfb8aa3b, v130
	v_exp_f32_e32 v130, v130
	v_add_f32_e32 v126, v126, v166
	v_mul_f32_e32 v126, 0xbfb8aa3b, v126
	v_exp_f32_e32 v126, v126
	v_add_f32_e32 v130, 1.0, v130
	v_rcp_f32_e64 v130, -v130
	v_add_f32_e32 v131, v131, v163
	v_mul_f32_e32 v131, 0xbfb8aa3b, v131
	v_add_f32_e32 v126, 1.0, v126
	v_mul_f32_e32 v130, v170, v130
	v_add_f32_e32 v136, v130, v130
	v_mul_f32_e32 v136, 0x3fb8aa3b, v136
	v_exp_f32_e32 v136, v136
	v_exp_f32_e32 v131, v131
	v_lshlrev_b32_e32 v134, 16, v98
	v_add_f32_e32 v127, v127, v167
	v_sub_f32_e32 v136, 1.0, v136
	v_max_f32_e32 v136, 0x1e3ce508, v136
	v_mul_f32_e32 v137, v126, v136
	v_mul_f32_e32 v126, v126, v137
	v_rsq_f32_e32 v126, v126
	v_add_f32_e32 v131, 1.0, v131
	v_rcp_f32_e64 v131, -v131
	v_mul_f32_e32 v127, 0xbfb8aa3b, v127
	v_mul_f32_e32 v126, v136, v126
	v_mul_f32_e32 v126, v126, v134
	v_cvt_pk_bf16_f32 v126, v130, v126
	v_mul_f32_e32 v130, v171, v131
	v_add_f32_e32 v131, v130, v130
	v_mul_f32_e32 v131, 0x3fb8aa3b, v131
	v_exp_f32_e32 v131, v131
	v_exp_f32_e32 v127, v127
	v_add_f32_e32 v132, v132, v164
	v_mul_f32_e32 v132, 0xbfb8aa3b, v132
	v_sub_f32_e32 v131, 1.0, v131
	v_max_f32_e32 v131, 0x1e3ce508, v131
	v_add_f32_e32 v127, 1.0, v127
	v_exp_f32_e32 v132, v132
	v_mul_f32_e32 v134, v127, v131
	v_mul_f32_e32 v127, v127, v134
	v_rsq_f32_e32 v127, v127
	v_add_f32_e32 v132, 1.0, v132
	v_rcp_f32_e64 v132, -v132
	v_and_b32_e32 v98, 0xffff0000, v98
	v_mul_f32_e32 v127, v131, v127
	v_mul_f32_e32 v98, v127, v98
	v_cvt_pk_bf16_f32 v127, v130, v98
	v_add_f32_e32 v130, v133, v165
	v_mul_f32_e32 v130, 0xbfb8aa3b, v130
	v_mul_f32_e32 v132, v172, v132
	v_exp_f32_e32 v130, v130
	v_add_f32_e32 v134, v132, v132
	v_mul_f32_e32 v134, 0x3fb8aa3b, v134
	v_add_f32_e32 v128, v128, v168
	v_exp_f32_e32 v134, v134
	v_mul_f32_e32 v128, 0xbfb8aa3b, v128
	v_exp_f32_e32 v128, v128
	v_add_f32_e32 v130, 1.0, v130
	v_rcp_f32_e64 v130, -v130
	v_sub_f32_e32 v98, 1.0, v134
	v_max_f32_e32 v98, 0x1e3ce508, v98
	v_add_f32_e32 v128, 1.0, v128
	v_mul_f32_e32 v131, v128, v98
	v_mul_f32_e32 v130, v173, v130
	v_mul_f32_e32 v128, v128, v131
	v_add_f32_e32 v131, v130, v130
	v_mul_f32_e32 v131, 0x3fb8aa3b, v131
	v_add_f32_e32 v129, v129, v169
	v_exp_f32_e32 v131, v131
	v_mul_f32_e32 v129, 0xbfb8aa3b, v129
	v_exp_f32_e32 v129, v129
	v_rsq_f32_e32 v128, v128
	v_sub_f32_e32 v131, 1.0, v131
	v_max_f32_e32 v131, 0x1e3ce508, v131
	v_add_f32_e32 v129, 1.0, v129
	v_mul_f32_e32 v133, v129, v131
	v_mul_f32_e32 v129, v129, v133
	v_rsq_f32_e32 v129, v129
	v_lshlrev_b32_e32 v135, 16, v99
	v_mul_f32_e32 v98, v98, v128
	v_mul_f32_e32 v98, v98, v135
	v_and_b32_e32 v99, 0xffff0000, v99
	v_cvt_pk_bf16_f32 v128, v132, v98
	v_mul_f32_e32 v98, v131, v129
	v_mul_f32_e32 v98, v98, v99
	v_cvt_pk_bf16_f32 v129, v130, v98
	v_lshlrev_b64 v[98:99], 12, v[216:217]
	v_lshl_add_u64 v[98:99], v[204:205], 0, v[98:99]
	global_store_dwordx4 v[98:99], v[126:129], off
	v_add_f32_e32 v118, v118, v162
	v_mul_f32_e32 v118, 0xbfb8aa3b, v118
	v_exp_f32_e32 v118, v118
	v_add_f32_e32 v114, v114, v166
	v_mul_f32_e32 v114, 0xbfb8aa3b, v114
	v_exp_f32_e32 v114, v114
	v_add_f32_e32 v118, 1.0, v118
	v_rcp_f32_e64 v118, -v118
	v_add_f32_e32 v119, v119, v163
	v_mul_f32_e32 v119, 0xbfb8aa3b, v119
	v_add_f32_e32 v114, 1.0, v114
	v_mul_f32_e32 v118, v170, v118
	v_add_f32_e32 v128, v118, v118
	v_mul_f32_e32 v128, 0x3fb8aa3b, v128
	v_exp_f32_e32 v128, v128
	v_exp_f32_e32 v119, v119
	v_lshlrev_b32_e32 v126, 16, v86
	v_add_f32_e32 v115, v115, v167
	v_sub_f32_e32 v128, 1.0, v128
	v_max_f32_e32 v128, 0x1e3ce508, v128
	v_mul_f32_e32 v129, v114, v128
	v_mul_f32_e32 v114, v114, v129
	v_rsq_f32_e32 v114, v114
	v_add_f32_e32 v119, 1.0, v119
	v_rcp_f32_e64 v119, -v119
	v_mul_f32_e32 v115, 0xbfb8aa3b, v115
	v_mul_f32_e32 v114, v128, v114
	v_mul_f32_e32 v114, v114, v126
	v_cvt_pk_bf16_f32 v114, v118, v114
	v_mul_f32_e32 v118, v171, v119
	v_add_f32_e32 v119, v118, v118
	v_mul_f32_e32 v119, 0x3fb8aa3b, v119
	v_exp_f32_e32 v119, v119
	v_exp_f32_e32 v115, v115
	v_add_f32_e32 v120, v120, v164
	v_mul_f32_e32 v120, 0xbfb8aa3b, v120
	v_sub_f32_e32 v119, 1.0, v119
	v_max_f32_e32 v119, 0x1e3ce508, v119
	v_add_f32_e32 v115, 1.0, v115
	v_exp_f32_e32 v120, v120
	v_mul_f32_e32 v126, v115, v119
	v_mul_f32_e32 v115, v115, v126
	v_rsq_f32_e32 v115, v115
	v_add_f32_e32 v120, 1.0, v120
	v_rcp_f32_e64 v120, -v120
	v_and_b32_e32 v86, 0xffff0000, v86
	v_mul_f32_e32 v115, v119, v115
	v_mul_f32_e32 v86, v115, v86
	v_cvt_pk_bf16_f32 v115, v118, v86
	v_add_f32_e32 v118, v121, v165
	v_mul_f32_e32 v118, 0xbfb8aa3b, v118
	v_mul_f32_e32 v120, v172, v120
	v_exp_f32_e32 v118, v118
	v_add_f32_e32 v126, v120, v120
	v_mul_f32_e32 v126, 0x3fb8aa3b, v126
	v_add_f32_e32 v116, v116, v168
	v_exp_f32_e32 v126, v126
	v_mul_f32_e32 v116, 0xbfb8aa3b, v116
	v_exp_f32_e32 v116, v116
	v_add_f32_e32 v118, 1.0, v118
	v_rcp_f32_e64 v118, -v118
	v_sub_f32_e32 v86, 1.0, v126
	v_max_f32_e32 v86, 0x1e3ce508, v86
	v_add_f32_e32 v116, 1.0, v116
	v_mul_f32_e32 v119, v116, v86
	v_mul_f32_e32 v118, v173, v118
	v_mul_f32_e32 v116, v116, v119
	v_add_f32_e32 v119, v118, v118
	v_mul_f32_e32 v119, 0x3fb8aa3b, v119
	v_add_f32_e32 v117, v117, v169
	v_exp_f32_e32 v119, v119
	v_mul_f32_e32 v117, 0xbfb8aa3b, v117
	v_exp_f32_e32 v117, v117
	v_rsq_f32_e32 v116, v116
	v_sub_f32_e32 v119, 1.0, v119
	v_max_f32_e32 v119, 0x1e3ce508, v119
	v_add_f32_e32 v117, 1.0, v117
	v_mul_f32_e32 v121, v117, v119
	v_mul_f32_e32 v117, v117, v121
	v_rsq_f32_e32 v117, v117
	v_lshlrev_b32_e32 v127, 16, v87
	v_mul_f32_e32 v86, v86, v116
	v_mul_f32_e32 v86, v86, v127
	v_and_b32_e32 v87, 0xffff0000, v87
	v_cvt_pk_bf16_f32 v116, v120, v86
	v_mul_f32_e32 v86, v119, v117
	v_mul_f32_e32 v86, v86, v87
	v_cvt_pk_bf16_f32 v117, v118, v86
	v_lshlrev_b64 v[86:87], 12, v[214:215]
	v_lshl_add_u64 v[86:87], v[204:205], 0, v[86:87]
	global_store_dwordx4 v[86:87], v[114:117], off
	v_add_f32_e32 v106, v106, v162
	v_mul_f32_e32 v106, 0xbfb8aa3b, v106
	v_exp_f32_e32 v106, v106
	v_add_f32_e32 v102, v102, v166
	v_mul_f32_e32 v102, 0xbfb8aa3b, v102
	v_exp_f32_e32 v102, v102
	v_add_f32_e32 v106, 1.0, v106
	v_rcp_f32_e64 v106, -v106
	v_add_f32_e32 v107, v107, v163
	v_mul_f32_e32 v107, 0xbfb8aa3b, v107
	v_add_f32_e32 v102, 1.0, v102
	v_mul_f32_e32 v106, v170, v106
	v_add_f32_e32 v116, v106, v106
	v_mul_f32_e32 v116, 0x3fb8aa3b, v116
	v_exp_f32_e32 v116, v116
	v_exp_f32_e32 v107, v107
	v_lshlrev_b32_e32 v114, 16, v74
	v_add_f32_e32 v103, v103, v167
	v_sub_f32_e32 v116, 1.0, v116
	v_max_f32_e32 v116, 0x1e3ce508, v116
	v_mul_f32_e32 v117, v102, v116
	v_mul_f32_e32 v102, v102, v117
	v_rsq_f32_e32 v102, v102
	v_add_f32_e32 v107, 1.0, v107
	v_rcp_f32_e64 v107, -v107
	v_mul_f32_e32 v103, 0xbfb8aa3b, v103
	v_mul_f32_e32 v102, v116, v102
	v_mul_f32_e32 v102, v102, v114
	v_cvt_pk_bf16_f32 v102, v106, v102
	v_mul_f32_e32 v106, v171, v107
	v_add_f32_e32 v107, v106, v106
	v_mul_f32_e32 v107, 0x3fb8aa3b, v107
	v_exp_f32_e32 v107, v107
	v_exp_f32_e32 v103, v103
	v_add_f32_e32 v108, v108, v164
	v_mul_f32_e32 v108, 0xbfb8aa3b, v108
	v_sub_f32_e32 v107, 1.0, v107
	v_max_f32_e32 v107, 0x1e3ce508, v107
	v_add_f32_e32 v103, 1.0, v103
	v_exp_f32_e32 v108, v108
	v_mul_f32_e32 v114, v103, v107
	v_mul_f32_e32 v103, v103, v114
	v_rsq_f32_e32 v103, v103
	v_add_f32_e32 v108, 1.0, v108
	v_rcp_f32_e64 v108, -v108
	v_and_b32_e32 v74, 0xffff0000, v74
	v_mul_f32_e32 v103, v107, v103
	v_mul_f32_e32 v74, v103, v74
	v_cvt_pk_bf16_f32 v103, v106, v74
	v_add_f32_e32 v106, v109, v165
	v_mul_f32_e32 v106, 0xbfb8aa3b, v106
	v_mul_f32_e32 v108, v172, v108
	v_exp_f32_e32 v106, v106
	v_add_f32_e32 v114, v108, v108
	v_mul_f32_e32 v114, 0x3fb8aa3b, v114
	v_add_f32_e32 v104, v104, v168
	v_exp_f32_e32 v114, v114
	v_mul_f32_e32 v104, 0xbfb8aa3b, v104
	v_exp_f32_e32 v104, v104
	v_add_f32_e32 v106, 1.0, v106
	v_rcp_f32_e64 v106, -v106
	v_sub_f32_e32 v74, 1.0, v114
	v_max_f32_e32 v74, 0x1e3ce508, v74
	v_add_f32_e32 v104, 1.0, v104
	v_mul_f32_e32 v107, v104, v74
	v_mul_f32_e32 v106, v173, v106
	v_mul_f32_e32 v104, v104, v107
	v_add_f32_e32 v107, v106, v106
	v_mul_f32_e32 v107, 0x3fb8aa3b, v107
	v_add_f32_e32 v105, v105, v169
	v_exp_f32_e32 v107, v107
	v_mul_f32_e32 v105, 0xbfb8aa3b, v105
	v_exp_f32_e32 v105, v105
	v_rsq_f32_e32 v104, v104
	v_sub_f32_e32 v107, 1.0, v107
	v_max_f32_e32 v107, 0x1e3ce508, v107
	v_add_f32_e32 v105, 1.0, v105
	v_mul_f32_e32 v109, v105, v107
	v_mul_f32_e32 v105, v105, v109
	v_rsq_f32_e32 v105, v105
	v_lshlrev_b32_e32 v115, 16, v75
	v_mul_f32_e32 v74, v74, v104
	v_mul_f32_e32 v74, v74, v115
	v_and_b32_e32 v75, 0xffff0000, v75
	v_cvt_pk_bf16_f32 v104, v108, v74
	v_mul_f32_e32 v74, v107, v105
	v_mul_f32_e32 v74, v74, v75
	v_cvt_pk_bf16_f32 v105, v106, v74
	v_lshlrev_b64 v[74:75], 12, v[212:213]
	v_lshl_add_u64 v[74:75], v[204:205], 0, v[74:75]
	global_store_dwordx4 v[74:75], v[102:105], off
	v_add_f32_e32 v94, v94, v162
	v_mul_f32_e32 v94, 0xbfb8aa3b, v94
	v_exp_f32_e32 v94, v94
	v_add_f32_e32 v90, v90, v166
	v_mul_f32_e32 v90, 0xbfb8aa3b, v90
	v_exp_f32_e32 v90, v90
	v_add_f32_e32 v94, 1.0, v94
	v_rcp_f32_e64 v94, -v94
	v_add_f32_e32 v95, v95, v163
	v_mul_f32_e32 v95, 0xbfb8aa3b, v95
	v_add_f32_e32 v90, 1.0, v90
	v_mul_f32_e32 v94, v170, v94
	v_add_f32_e32 v104, v94, v94
	v_mul_f32_e32 v104, 0x3fb8aa3b, v104
	v_exp_f32_e32 v104, v104
	v_exp_f32_e32 v95, v95
	s_waitcnt vmcnt(9)
	v_lshlrev_b32_e32 v102, 16, v70
	v_add_f32_e32 v91, v91, v167
	v_sub_f32_e32 v104, 1.0, v104
	v_max_f32_e32 v104, 0x1e3ce508, v104
	v_mul_f32_e32 v105, v90, v104
	v_mul_f32_e32 v90, v90, v105
	v_rsq_f32_e32 v90, v90
	v_add_f32_e32 v95, 1.0, v95
	v_rcp_f32_e64 v95, -v95
	v_mul_f32_e32 v91, 0xbfb8aa3b, v91
	v_mul_f32_e32 v90, v104, v90
	v_mul_f32_e32 v90, v90, v102
	v_cvt_pk_bf16_f32 v90, v94, v90
	v_mul_f32_e32 v94, v171, v95
	v_add_f32_e32 v95, v94, v94
	v_mul_f32_e32 v95, 0x3fb8aa3b, v95
	v_exp_f32_e32 v95, v95
	v_exp_f32_e32 v91, v91
	v_add_f32_e32 v96, v96, v164
	v_mul_f32_e32 v96, 0xbfb8aa3b, v96
	v_sub_f32_e32 v95, 1.0, v95
	v_max_f32_e32 v95, 0x1e3ce508, v95
	v_add_f32_e32 v91, 1.0, v91
	v_exp_f32_e32 v96, v96
	v_mul_f32_e32 v102, v91, v95
	v_mul_f32_e32 v91, v91, v102
	v_rsq_f32_e32 v91, v91
	v_add_f32_e32 v96, 1.0, v96
	v_rcp_f32_e64 v96, -v96
	v_and_b32_e32 v70, 0xffff0000, v70
	v_mul_f32_e32 v91, v95, v91
	v_mul_f32_e32 v70, v91, v70
	v_cvt_pk_bf16_f32 v91, v94, v70
	v_add_f32_e32 v94, v97, v165
	v_mul_f32_e32 v94, 0xbfb8aa3b, v94
	v_mul_f32_e32 v96, v172, v96
	v_exp_f32_e32 v94, v94
	v_add_f32_e32 v102, v96, v96
	v_mul_f32_e32 v102, 0x3fb8aa3b, v102
	v_add_f32_e32 v92, v92, v168
	v_exp_f32_e32 v102, v102
	v_mul_f32_e32 v92, 0xbfb8aa3b, v92
	v_exp_f32_e32 v92, v92
	v_add_f32_e32 v94, 1.0, v94
	v_rcp_f32_e64 v94, -v94
	v_sub_f32_e32 v70, 1.0, v102
	v_max_f32_e32 v70, 0x1e3ce508, v70
	v_add_f32_e32 v92, 1.0, v92
	v_mul_f32_e32 v95, v92, v70
	v_mul_f32_e32 v94, v173, v94
	v_mul_f32_e32 v92, v92, v95
	v_add_f32_e32 v95, v94, v94
	v_mul_f32_e32 v95, 0x3fb8aa3b, v95
	v_add_f32_e32 v93, v93, v169
	v_exp_f32_e32 v95, v95
	v_mul_f32_e32 v93, 0xbfb8aa3b, v93
	v_exp_f32_e32 v93, v93
	v_rsq_f32_e32 v92, v92
	v_sub_f32_e32 v95, 1.0, v95
	v_max_f32_e32 v95, 0x1e3ce508, v95
	v_add_f32_e32 v93, 1.0, v93
	v_mul_f32_e32 v97, v93, v95
	v_mul_f32_e32 v93, v93, v97
	v_rsq_f32_e32 v93, v93
	v_lshlrev_b32_e32 v103, 16, v71
	v_mul_f32_e32 v70, v70, v92
	v_mul_f32_e32 v70, v70, v103
	v_and_b32_e32 v71, 0xffff0000, v71
	v_cvt_pk_bf16_f32 v92, v96, v70
	v_mul_f32_e32 v70, v95, v93
	v_mul_f32_e32 v70, v70, v71
	v_cvt_pk_bf16_f32 v93, v94, v70
	v_lshlrev_b64 v[70:71], 12, v[202:203]
	v_lshl_add_u64 v[70:71], v[204:205], 0, v[70:71]
	global_store_dwordx4 v[70:71], v[90:93], off
	v_add_f32_e32 v82, v82, v162
	v_mul_f32_e32 v82, 0xbfb8aa3b, v82
	v_exp_f32_e32 v82, v82
	v_add_f32_e32 v78, v78, v166
	v_mul_f32_e32 v78, 0xbfb8aa3b, v78
	v_exp_f32_e32 v78, v78
	v_add_f32_e32 v82, 1.0, v82
	v_rcp_f32_e64 v82, -v82
	v_add_f32_e32 v83, v83, v163
	v_mul_f32_e32 v83, 0xbfb8aa3b, v83
	v_add_f32_e32 v78, 1.0, v78
	v_mul_f32_e32 v82, v170, v82
	v_add_f32_e32 v92, v82, v82
	v_mul_f32_e32 v92, 0x3fb8aa3b, v92
	v_exp_f32_e32 v92, v92
	v_exp_f32_e32 v83, v83
	v_lshlrev_b32_e32 v90, 16, v66
	v_add_f32_e32 v79, v79, v167
	v_sub_f32_e32 v92, 1.0, v92
	v_max_f32_e32 v92, 0x1e3ce508, v92
	v_mul_f32_e32 v93, v78, v92
	v_mul_f32_e32 v78, v78, v93
	v_rsq_f32_e32 v78, v78
	v_add_f32_e32 v83, 1.0, v83
	v_rcp_f32_e64 v83, -v83
	v_mul_f32_e32 v79, 0xbfb8aa3b, v79
	v_mul_f32_e32 v78, v92, v78
	v_mul_f32_e32 v78, v78, v90
	v_cvt_pk_bf16_f32 v78, v82, v78
	v_mul_f32_e32 v82, v171, v83
	v_add_f32_e32 v83, v82, v82
	v_mul_f32_e32 v83, 0x3fb8aa3b, v83
	v_exp_f32_e32 v83, v83
	v_exp_f32_e32 v79, v79
	v_add_f32_e32 v84, v84, v164
	v_mul_f32_e32 v84, 0xbfb8aa3b, v84
	v_sub_f32_e32 v83, 1.0, v83
	v_max_f32_e32 v83, 0x1e3ce508, v83
	v_add_f32_e32 v79, 1.0, v79
	v_exp_f32_e32 v84, v84
	v_mul_f32_e32 v90, v79, v83
	v_mul_f32_e32 v79, v79, v90
	v_rsq_f32_e32 v79, v79
	v_add_f32_e32 v84, 1.0, v84
	v_rcp_f32_e64 v84, -v84
	v_and_b32_e32 v66, 0xffff0000, v66
	v_mul_f32_e32 v79, v83, v79
	v_mul_f32_e32 v66, v79, v66
	v_cvt_pk_bf16_f32 v79, v82, v66
	v_add_f32_e32 v82, v85, v165
	v_mul_f32_e32 v82, 0xbfb8aa3b, v82
	v_mul_f32_e32 v84, v172, v84
	v_exp_f32_e32 v82, v82
	v_add_f32_e32 v90, v84, v84
	v_mul_f32_e32 v90, 0x3fb8aa3b, v90
	v_add_f32_e32 v80, v80, v168
	v_exp_f32_e32 v90, v90
	v_mul_f32_e32 v80, 0xbfb8aa3b, v80
	v_exp_f32_e32 v80, v80
	v_add_f32_e32 v82, 1.0, v82
	v_rcp_f32_e64 v82, -v82
	v_sub_f32_e32 v66, 1.0, v90
	v_max_f32_e32 v66, 0x1e3ce508, v66
	v_add_f32_e32 v80, 1.0, v80
	v_mul_f32_e32 v83, v80, v66
	v_mul_f32_e32 v82, v173, v82
	v_mul_f32_e32 v80, v80, v83
	v_add_f32_e32 v83, v82, v82
	v_mul_f32_e32 v83, 0x3fb8aa3b, v83
	v_add_f32_e32 v81, v81, v169
	v_exp_f32_e32 v83, v83
	v_mul_f32_e32 v81, 0xbfb8aa3b, v81
	v_exp_f32_e32 v81, v81
	v_rsq_f32_e32 v80, v80
	v_sub_f32_e32 v83, 1.0, v83
	v_max_f32_e32 v83, 0x1e3ce508, v83
	v_add_f32_e32 v81, 1.0, v81
	v_mul_f32_e32 v85, v81, v83
	v_mul_f32_e32 v81, v81, v85
	v_rsq_f32_e32 v81, v81
	v_lshlrev_b32_e32 v91, 16, v67
	v_mul_f32_e32 v66, v66, v80
	v_mul_f32_e32 v66, v66, v91
	v_and_b32_e32 v67, 0xffff0000, v67
	v_cvt_pk_bf16_f32 v80, v84, v66
	v_mul_f32_e32 v66, v83, v81
	v_mul_f32_e32 v66, v66, v67
	v_cvt_pk_bf16_f32 v81, v82, v66
	v_lshlrev_b64 v[66:67], 12, v[200:201]
	v_lshl_add_u64 v[66:67], v[204:205], 0, v[66:67]
	global_store_dwordx4 v[66:67], v[78:81], off
	v_lshlrev_b32_e32 v95, 16, v160
	v_and_b32_e32 v96, 0xffff0000, v160
	v_lshlrev_b32_e32 v97, 16, v161
	v_and_b32_e32 v94, 0xffff0000, v161
	s_waitcnt vmcnt(6)
	v_mov_b32_e32 v90, v146
	v_mov_b32_e32 v91, v147
	v_mov_b32_e32 v92, v148
	v_mov_b32_e32 v93, v149
	v_mov_b32_e32 v82, v156
	v_mov_b32_e32 v83, v157
	v_mov_b32_e32 v84, v158
	v_mov_b32_e32 v85, v159
	v_mov_b32_e32 v78, v150
	v_mov_b32_e32 v79, v151
	v_mov_b32_e32 v80, v152
	v_mov_b32_e32 v81, v153
	v_add_f32_e32 v62, v62, v90
	v_mul_f32_e32 v62, 0xbfb8aa3b, v62
	v_exp_f32_e32 v62, v62
	v_add_f32_e32 v58, v58, v78
	v_mul_f32_e32 v58, 0xbfb8aa3b, v58
	v_exp_f32_e32 v58, v58
	v_add_f32_e32 v62, 1.0, v62
	v_rcp_f32_e64 v62, -v62
	v_add_f32_e32 v59, v59, v79
	v_add_f32_e32 v58, 1.0, v58
	v_mul_f32_e32 v59, 0xbfb8aa3b, v59
	v_mul_f32_e32 v62, v82, v62
	v_add_f32_e32 v102, v62, v62
	v_mul_f32_e32 v102, 0x3fb8aa3b, v102
	v_exp_f32_e32 v102, v102
	v_exp_f32_e32 v59, v59
	v_add_f32_e32 v60, v60, v80
	v_mul_f32_e32 v60, 0xbfb8aa3b, v60
	v_sub_f32_e32 v102, 1.0, v102
	v_max_f32_e32 v102, 0x1e3ce508, v102
	v_mul_f32_e32 v103, v58, v102
	v_mul_f32_e32 v58, v58, v103
	v_rsq_f32_e32 v58, v58
	v_add_f32_e32 v59, 1.0, v59
	v_exp_f32_e32 v60, v60
	v_add_f32_e32 v61, v61, v81
	v_mul_f32_e32 v58, v102, v58
	v_mul_f32_e32 v58, v58, v95
	v_cvt_pk_bf16_f32 v58, v62, v58
	v_add_f32_e32 v62, v63, v91
	v_mul_f32_e32 v62, 0xbfb8aa3b, v62
	v_exp_f32_e32 v62, v62
	v_add_f32_e32 v60, 1.0, v60
	v_mul_f32_e32 v61, 0xbfb8aa3b, v61
	v_exp_f32_e32 v61, v61
	v_add_f32_e32 v62, 1.0, v62
	v_rcp_f32_e64 v62, -v62
	v_add_f32_e32 v61, 1.0, v61
	v_mul_f32_e32 v62, v83, v62
	v_add_f32_e32 v63, v62, v62
	v_mul_f32_e32 v63, 0x3fb8aa3b, v63
	v_exp_f32_e32 v63, v63
	s_nop 0
	v_sub_f32_e32 v63, 1.0, v63
	v_max_f32_e32 v63, 0x1e3ce508, v63
	v_mul_f32_e32 v95, v59, v63
	v_mul_f32_e32 v59, v59, v95
	v_rsq_f32_e32 v59, v59
	s_nop 0
	v_mul_f32_e32 v59, v63, v59
	v_mul_f32_e32 v59, v59, v96
	v_cvt_pk_bf16_f32 v59, v62, v59
	v_add_f32_e32 v62, v64, v92
	v_mul_f32_e32 v62, 0xbfb8aa3b, v62
	v_exp_f32_e32 v62, v62
	s_nop 0
	v_add_f32_e32 v62, 1.0, v62
	v_rcp_f32_e64 v62, -v62
	s_nop 0
	v_mul_f32_e32 v62, v84, v62
	v_add_f32_e32 v63, v62, v62
	v_mul_f32_e32 v63, 0x3fb8aa3b, v63
	v_exp_f32_e32 v63, v63
	s_nop 0
	v_sub_f32_e32 v63, 1.0, v63
	v_max_f32_e32 v63, 0x1e3ce508, v63
	v_mul_f32_e32 v64, v60, v63
	v_mul_f32_e32 v60, v60, v64
	v_rsq_f32_e32 v60, v60
	s_nop 0
	v_mul_f32_e32 v60, v63, v60
	v_mul_f32_e32 v60, v60, v97
	v_cvt_pk_bf16_f32 v60, v62, v60
	v_add_f32_e32 v62, v65, v93
	v_mul_f32_e32 v62, 0xbfb8aa3b, v62
	v_exp_f32_e32 v62, v62
	s_nop 0
	v_add_f32_e32 v62, 1.0, v62
	v_rcp_f32_e64 v62, -v62
	s_nop 0
	v_mul_f32_e32 v62, v85, v62
	v_add_f32_e32 v63, v62, v62
	v_mul_f32_e32 v63, 0x3fb8aa3b, v63
	v_exp_f32_e32 v63, v63
	s_nop 0
	v_sub_f32_e32 v63, 1.0, v63
	v_max_f32_e32 v63, 0x1e3ce508, v63
	v_mul_f32_e32 v64, v61, v63
	v_mul_f32_e32 v61, v61, v64
	v_rsq_f32_e32 v61, v61
	s_nop 0
	v_mul_f32_e32 v61, v63, v61
	v_mul_f32_e32 v61, v61, v94
	v_cvt_pk_bf16_f32 v61, v62, v61
	global_store_dwordx4 v[154:155], v[58:61], off offset:16
	v_add_f32_e32 v54, v54, v90
	v_mul_f32_e32 v54, 0xbfb8aa3b, v54
	v_exp_f32_e32 v54, v54
	v_add_f32_e32 v50, v50, v78
	v_mul_f32_e32 v50, 0xbfb8aa3b, v50
	v_exp_f32_e32 v50, v50
	v_add_f32_e32 v54, 1.0, v54
	v_rcp_f32_e64 v54, -v54
	v_add_f32_e32 v55, v55, v91
	v_mul_f32_e32 v55, 0xbfb8aa3b, v55
	v_add_f32_e32 v50, 1.0, v50
	v_mul_f32_e32 v54, v82, v54
	v_add_f32_e32 v61, v54, v54
	v_mul_f32_e32 v61, 0x3fb8aa3b, v61
	v_exp_f32_e32 v61, v61
	v_exp_f32_e32 v55, v55
	v_lshlrev_b32_e32 v58, 16, v124
	v_add_f32_e32 v51, v51, v79
	v_sub_f32_e32 v61, 1.0, v61
	v_max_f32_e32 v61, 0x1e3ce508, v61
	v_mul_f32_e32 v62, v50, v61
	v_mul_f32_e32 v50, v50, v62
	v_rsq_f32_e32 v50, v50
	v_add_f32_e32 v55, 1.0, v55
	v_rcp_f32_e64 v55, -v55
	v_mul_f32_e32 v51, 0xbfb8aa3b, v51
	v_mul_f32_e32 v50, v61, v50
	v_mul_f32_e32 v50, v50, v58
	v_cvt_pk_bf16_f32 v50, v54, v50
	v_mul_f32_e32 v54, v83, v55
	v_add_f32_e32 v55, v54, v54
	v_mul_f32_e32 v55, 0x3fb8aa3b, v55
	v_exp_f32_e32 v55, v55
	v_exp_f32_e32 v51, v51
	v_add_f32_e32 v56, v56, v92
	v_mul_f32_e32 v56, 0xbfb8aa3b, v56
	v_sub_f32_e32 v55, 1.0, v55
	v_exp_f32_e32 v56, v56
	v_max_f32_e32 v55, 0x1e3ce508, v55
	v_add_f32_e32 v51, 1.0, v51
	v_mul_f32_e32 v58, v51, v55
	v_mul_f32_e32 v51, v51, v58
	v_rsq_f32_e32 v51, v51
	v_add_f32_e32 v56, 1.0, v56
	v_rcp_f32_e64 v56, -v56
	v_add_f32_e32 v52, v52, v80
	v_mul_f32_e32 v51, v55, v51
	v_add_f32_e32 v55, v57, v93
	v_mul_f32_e32 v55, 0xbfb8aa3b, v55
	v_mul_f32_e32 v56, v84, v56
	v_exp_f32_e32 v55, v55
	v_add_f32_e32 v58, v56, v56
	v_mul_f32_e32 v58, 0x3fb8aa3b, v58
	v_exp_f32_e32 v58, v58
	v_mul_f32_e32 v52, 0xbfb8aa3b, v52
	v_exp_f32_e32 v52, v52
	v_add_f32_e32 v55, 1.0, v55
	v_and_b32_e32 v59, 0xffff0000, v124
	v_rcp_f32_e64 v55, -v55
	v_mul_f32_e32 v51, v51, v59
	v_cvt_pk_bf16_f32 v51, v54, v51
	v_sub_f32_e32 v54, 1.0, v58
	v_max_f32_e32 v54, 0x1e3ce508, v54
	v_add_f32_e32 v52, 1.0, v52
	v_mul_f32_e32 v57, v52, v54
	v_mul_f32_e32 v55, v85, v55
	v_mul_f32_e32 v52, v52, v57
	v_add_f32_e32 v57, v55, v55
	v_mul_f32_e32 v57, 0x3fb8aa3b, v57
	v_add_f32_e32 v53, v53, v81
	v_exp_f32_e32 v57, v57
	v_mul_f32_e32 v53, 0xbfb8aa3b, v53
	v_exp_f32_e32 v53, v53
	v_rsq_f32_e32 v52, v52
	v_sub_f32_e32 v57, 1.0, v57
	v_max_f32_e32 v57, 0x1e3ce508, v57
	v_add_f32_e32 v53, 1.0, v53
	v_mul_f32_e32 v58, v53, v57
	v_mul_f32_e32 v53, v53, v58
	v_rsq_f32_e32 v53, v53
	v_lshlrev_b32_e32 v60, 16, v125
	v_and_b32_e32 v62, 0xffff0000, v125
	v_mul_f32_e32 v52, v54, v52
	v_mul_f32_e32 v53, v57, v53
	v_mul_f32_e32 v52, v52, v60
	v_mul_f32_e32 v53, v53, v62
	v_cvt_pk_bf16_f32 v52, v56, v52
	v_cvt_pk_bf16_f32 v53, v55, v53
	global_store_dwordx4 v[122:123], v[50:53], off offset:16
	v_add_f32_e32 v46, v46, v90
	v_mul_f32_e32 v46, 0xbfb8aa3b, v46
	v_exp_f32_e32 v46, v46
	v_add_f32_e32 v42, v42, v78
	v_mul_f32_e32 v42, 0xbfb8aa3b, v42
	v_exp_f32_e32 v42, v42
	v_add_f32_e32 v46, 1.0, v46
	v_rcp_f32_e64 v46, -v46
	v_add_f32_e32 v47, v47, v91
	v_mul_f32_e32 v47, 0xbfb8aa3b, v47
	v_add_f32_e32 v42, 1.0, v42
	v_mul_f32_e32 v46, v82, v46
	v_add_f32_e32 v53, v46, v46
	v_mul_f32_e32 v53, 0x3fb8aa3b, v53
	v_exp_f32_e32 v53, v53
	v_exp_f32_e32 v47, v47
	v_lshlrev_b32_e32 v50, 16, v112
	v_add_f32_e32 v43, v43, v79
	v_sub_f32_e32 v53, 1.0, v53
	v_max_f32_e32 v53, 0x1e3ce508, v53
	v_mul_f32_e32 v54, v42, v53
	v_mul_f32_e32 v42, v42, v54
	v_rsq_f32_e32 v42, v42
	v_add_f32_e32 v47, 1.0, v47
	v_rcp_f32_e64 v47, -v47
	v_mul_f32_e32 v43, 0xbfb8aa3b, v43
	v_mul_f32_e32 v42, v53, v42
	v_mul_f32_e32 v42, v42, v50
	v_cvt_pk_bf16_f32 v42, v46, v42
	v_mul_f32_e32 v46, v83, v47
	v_add_f32_e32 v47, v46, v46
	v_mul_f32_e32 v47, 0x3fb8aa3b, v47
	v_exp_f32_e32 v47, v47
	v_exp_f32_e32 v43, v43
	v_add_f32_e32 v48, v48, v92
	v_mul_f32_e32 v48, 0xbfb8aa3b, v48
	v_sub_f32_e32 v47, 1.0, v47
	v_exp_f32_e32 v48, v48
	v_max_f32_e32 v47, 0x1e3ce508, v47
	v_add_f32_e32 v43, 1.0, v43
	v_mul_f32_e32 v50, v43, v47
	v_mul_f32_e32 v43, v43, v50
	v_rsq_f32_e32 v43, v43
	v_add_f32_e32 v48, 1.0, v48
	v_rcp_f32_e64 v48, -v48
	v_add_f32_e32 v44, v44, v80
	v_mul_f32_e32 v43, v47, v43
	v_add_f32_e32 v47, v49, v93
	v_mul_f32_e32 v47, 0xbfb8aa3b, v47
	v_mul_f32_e32 v48, v84, v48
	v_exp_f32_e32 v47, v47
	v_add_f32_e32 v50, v48, v48
	v_mul_f32_e32 v50, 0x3fb8aa3b, v50
	v_exp_f32_e32 v50, v50
	v_mul_f32_e32 v44, 0xbfb8aa3b, v44
	v_exp_f32_e32 v44, v44
	v_add_f32_e32 v47, 1.0, v47
	v_and_b32_e32 v51, 0xffff0000, v112
	v_rcp_f32_e64 v47, -v47
	v_mul_f32_e32 v43, v43, v51
	v_cvt_pk_bf16_f32 v43, v46, v43
	v_sub_f32_e32 v46, 1.0, v50
	v_max_f32_e32 v46, 0x1e3ce508, v46
	v_add_f32_e32 v44, 1.0, v44
	v_mul_f32_e32 v49, v44, v46
	v_mul_f32_e32 v47, v85, v47
	v_mul_f32_e32 v44, v44, v49
	v_add_f32_e32 v49, v47, v47
	v_mul_f32_e32 v49, 0x3fb8aa3b, v49
	v_add_f32_e32 v45, v45, v81
	v_exp_f32_e32 v49, v49
	v_mul_f32_e32 v45, 0xbfb8aa3b, v45
	v_exp_f32_e32 v45, v45
	v_rsq_f32_e32 v44, v44
	v_sub_f32_e32 v49, 1.0, v49
	v_max_f32_e32 v49, 0x1e3ce508, v49
	v_add_f32_e32 v45, 1.0, v45
	v_mul_f32_e32 v50, v45, v49
	v_mul_f32_e32 v45, v45, v50
	v_rsq_f32_e32 v45, v45
	v_lshlrev_b32_e32 v52, 16, v113
	v_and_b32_e32 v54, 0xffff0000, v113
	v_mul_f32_e32 v44, v46, v44
	v_mul_f32_e32 v45, v49, v45
	v_mul_f32_e32 v44, v44, v52
	v_mul_f32_e32 v45, v45, v54
	v_cvt_pk_bf16_f32 v44, v48, v44
	v_cvt_pk_bf16_f32 v45, v47, v45
	global_store_dwordx4 v[110:111], v[42:45], off offset:16
	v_add_f32_e32 v38, v38, v90
	v_mul_f32_e32 v38, 0xbfb8aa3b, v38
	v_exp_f32_e32 v38, v38
	v_add_f32_e32 v34, v34, v78
	v_mul_f32_e32 v34, 0xbfb8aa3b, v34
	v_exp_f32_e32 v34, v34
	v_add_f32_e32 v38, 1.0, v38
	v_rcp_f32_e64 v38, -v38
	v_add_f32_e32 v39, v39, v91
	v_mul_f32_e32 v39, 0xbfb8aa3b, v39
	v_add_f32_e32 v34, 1.0, v34
	v_mul_f32_e32 v38, v82, v38
	v_add_f32_e32 v45, v38, v38
	v_mul_f32_e32 v45, 0x3fb8aa3b, v45
	v_exp_f32_e32 v45, v45
	v_exp_f32_e32 v39, v39
	v_lshlrev_b32_e32 v42, 16, v100
	v_add_f32_e32 v35, v35, v79
	v_sub_f32_e32 v45, 1.0, v45
	v_max_f32_e32 v45, 0x1e3ce508, v45
	v_mul_f32_e32 v46, v34, v45
	v_mul_f32_e32 v34, v34, v46
	v_rsq_f32_e32 v34, v34
	v_add_f32_e32 v39, 1.0, v39
	v_rcp_f32_e64 v39, -v39
	v_mul_f32_e32 v35, 0xbfb8aa3b, v35
	v_mul_f32_e32 v34, v45, v34
	v_mul_f32_e32 v34, v34, v42
	v_cvt_pk_bf16_f32 v34, v38, v34
	v_mul_f32_e32 v38, v83, v39
	v_add_f32_e32 v39, v38, v38
	v_mul_f32_e32 v39, 0x3fb8aa3b, v39
	v_exp_f32_e32 v39, v39
	v_exp_f32_e32 v35, v35
	v_add_f32_e32 v40, v40, v92
	v_mul_f32_e32 v40, 0xbfb8aa3b, v40
	v_sub_f32_e32 v39, 1.0, v39
	v_exp_f32_e32 v40, v40
	v_max_f32_e32 v39, 0x1e3ce508, v39
	v_add_f32_e32 v35, 1.0, v35
	v_mul_f32_e32 v42, v35, v39
	v_mul_f32_e32 v35, v35, v42
	v_rsq_f32_e32 v35, v35
	v_add_f32_e32 v40, 1.0, v40
	v_rcp_f32_e64 v40, -v40
	v_add_f32_e32 v36, v36, v80
	v_mul_f32_e32 v35, v39, v35
	v_add_f32_e32 v39, v41, v93
	v_mul_f32_e32 v39, 0xbfb8aa3b, v39
	v_mul_f32_e32 v40, v84, v40
	v_exp_f32_e32 v39, v39
	v_add_f32_e32 v42, v40, v40
	v_mul_f32_e32 v42, 0x3fb8aa3b, v42
	v_exp_f32_e32 v42, v42
	v_mul_f32_e32 v36, 0xbfb8aa3b, v36
	v_exp_f32_e32 v36, v36
	v_add_f32_e32 v39, 1.0, v39
	v_and_b32_e32 v43, 0xffff0000, v100
	v_rcp_f32_e64 v39, -v39
	v_mul_f32_e32 v35, v35, v43
	v_cvt_pk_bf16_f32 v35, v38, v35
	v_sub_f32_e32 v38, 1.0, v42
	v_max_f32_e32 v38, 0x1e3ce508, v38
	v_add_f32_e32 v36, 1.0, v36
	v_mul_f32_e32 v41, v36, v38
	v_mul_f32_e32 v39, v85, v39
	v_mul_f32_e32 v36, v36, v41
	v_add_f32_e32 v41, v39, v39
	v_mul_f32_e32 v41, 0x3fb8aa3b, v41
	v_add_f32_e32 v37, v37, v81
	v_exp_f32_e32 v41, v41
	v_mul_f32_e32 v37, 0xbfb8aa3b, v37
	v_exp_f32_e32 v37, v37
	v_rsq_f32_e32 v36, v36
	v_sub_f32_e32 v41, 1.0, v41
	v_max_f32_e32 v41, 0x1e3ce508, v41
	v_add_f32_e32 v37, 1.0, v37
	v_mul_f32_e32 v42, v37, v41
	v_mul_f32_e32 v37, v37, v42
	v_rsq_f32_e32 v37, v37
	v_lshlrev_b32_e32 v44, 16, v101
	v_and_b32_e32 v46, 0xffff0000, v101
	v_mul_f32_e32 v36, v38, v36
	v_mul_f32_e32 v37, v41, v37
	v_mul_f32_e32 v36, v36, v44
	v_mul_f32_e32 v37, v37, v46
	v_cvt_pk_bf16_f32 v36, v40, v36
	v_cvt_pk_bf16_f32 v37, v39, v37
	global_store_dwordx4 v[98:99], v[34:37], off offset:16
	v_add_f32_e32 v30, v30, v90
	v_mul_f32_e32 v30, 0xbfb8aa3b, v30
	v_exp_f32_e32 v30, v30
	v_add_f32_e32 v26, v26, v78
	v_mul_f32_e32 v26, 0xbfb8aa3b, v26
	v_exp_f32_e32 v26, v26
	v_add_f32_e32 v30, 1.0, v30
	v_rcp_f32_e64 v30, -v30
	v_add_f32_e32 v31, v31, v91
	v_mul_f32_e32 v31, 0xbfb8aa3b, v31
	v_add_f32_e32 v26, 1.0, v26
	v_mul_f32_e32 v30, v82, v30
	v_add_f32_e32 v37, v30, v30
	v_mul_f32_e32 v37, 0x3fb8aa3b, v37
	v_exp_f32_e32 v37, v37
	v_exp_f32_e32 v31, v31
	v_lshlrev_b32_e32 v34, 16, v88
	v_add_f32_e32 v27, v27, v79
	v_sub_f32_e32 v37, 1.0, v37
	v_max_f32_e32 v37, 0x1e3ce508, v37
	v_mul_f32_e32 v38, v26, v37
	v_mul_f32_e32 v26, v26, v38
	v_rsq_f32_e32 v26, v26
	v_add_f32_e32 v31, 1.0, v31
	v_rcp_f32_e64 v31, -v31
	v_mul_f32_e32 v27, 0xbfb8aa3b, v27
	v_mul_f32_e32 v26, v37, v26
	v_mul_f32_e32 v26, v26, v34
	v_cvt_pk_bf16_f32 v26, v30, v26
	v_mul_f32_e32 v30, v83, v31
	v_add_f32_e32 v31, v30, v30
	v_mul_f32_e32 v31, 0x3fb8aa3b, v31
	v_exp_f32_e32 v31, v31
	v_exp_f32_e32 v27, v27
	v_add_f32_e32 v32, v32, v92
	v_mul_f32_e32 v32, 0xbfb8aa3b, v32
	v_sub_f32_e32 v31, 1.0, v31
	v_exp_f32_e32 v32, v32
	v_max_f32_e32 v31, 0x1e3ce508, v31
	v_add_f32_e32 v27, 1.0, v27
	v_mul_f32_e32 v34, v27, v31
	v_mul_f32_e32 v27, v27, v34
	v_rsq_f32_e32 v27, v27
	v_add_f32_e32 v32, 1.0, v32
	v_rcp_f32_e64 v32, -v32
	v_add_f32_e32 v28, v28, v80
	v_mul_f32_e32 v27, v31, v27
	v_add_f32_e32 v31, v33, v93
	v_mul_f32_e32 v31, 0xbfb8aa3b, v31
	v_mul_f32_e32 v32, v84, v32
	v_exp_f32_e32 v31, v31
	v_add_f32_e32 v34, v32, v32
	v_mul_f32_e32 v34, 0x3fb8aa3b, v34
	v_exp_f32_e32 v34, v34
	v_mul_f32_e32 v28, 0xbfb8aa3b, v28
	v_exp_f32_e32 v28, v28
	v_add_f32_e32 v31, 1.0, v31
	v_and_b32_e32 v35, 0xffff0000, v88
	v_rcp_f32_e64 v31, -v31
	v_mul_f32_e32 v27, v27, v35
	v_cvt_pk_bf16_f32 v27, v30, v27
	v_sub_f32_e32 v30, 1.0, v34
	v_max_f32_e32 v30, 0x1e3ce508, v30
	v_add_f32_e32 v28, 1.0, v28
	v_mul_f32_e32 v33, v28, v30
	v_mul_f32_e32 v31, v85, v31
	v_mul_f32_e32 v28, v28, v33
	v_add_f32_e32 v33, v31, v31
	v_mul_f32_e32 v33, 0x3fb8aa3b, v33
	v_add_f32_e32 v29, v29, v81
	v_exp_f32_e32 v33, v33
	v_mul_f32_e32 v29, 0xbfb8aa3b, v29
	v_exp_f32_e32 v29, v29
	v_rsq_f32_e32 v28, v28
	v_sub_f32_e32 v33, 1.0, v33
	v_max_f32_e32 v33, 0x1e3ce508, v33
	v_add_f32_e32 v29, 1.0, v29
	v_mul_f32_e32 v34, v29, v33
	v_mul_f32_e32 v29, v29, v34
	v_rsq_f32_e32 v29, v29
	v_lshlrev_b32_e32 v36, 16, v89
	v_and_b32_e32 v38, 0xffff0000, v89
	v_mul_f32_e32 v28, v30, v28
	v_mul_f32_e32 v29, v33, v29
	v_mul_f32_e32 v28, v28, v36
	v_mul_f32_e32 v29, v29, v38
	v_cvt_pk_bf16_f32 v28, v32, v28
	v_cvt_pk_bf16_f32 v29, v31, v29
	global_store_dwordx4 v[86:87], v[26:29], off offset:16
	v_add_f32_e32 v22, v22, v90
	v_mul_f32_e32 v22, 0xbfb8aa3b, v22
	v_exp_f32_e32 v22, v22
	v_add_f32_e32 v18, v18, v78
	v_mul_f32_e32 v18, 0xbfb8aa3b, v18
	v_exp_f32_e32 v18, v18
	v_add_f32_e32 v22, 1.0, v22
	v_rcp_f32_e64 v22, -v22
	v_add_f32_e32 v23, v23, v91
	v_mul_f32_e32 v23, 0xbfb8aa3b, v23
	v_add_f32_e32 v18, 1.0, v18
	v_mul_f32_e32 v22, v82, v22
	v_add_f32_e32 v29, v22, v22
	v_mul_f32_e32 v29, 0x3fb8aa3b, v29
	v_exp_f32_e32 v29, v29
	v_exp_f32_e32 v23, v23
	v_lshlrev_b32_e32 v26, 16, v76
	v_add_f32_e32 v19, v19, v79
	v_sub_f32_e32 v29, 1.0, v29
	v_max_f32_e32 v29, 0x1e3ce508, v29
	v_mul_f32_e32 v30, v18, v29
	v_mul_f32_e32 v18, v18, v30
	v_rsq_f32_e32 v18, v18
	v_add_f32_e32 v23, 1.0, v23
	v_rcp_f32_e64 v23, -v23
	v_mul_f32_e32 v19, 0xbfb8aa3b, v19
	v_mul_f32_e32 v18, v29, v18
	v_mul_f32_e32 v18, v18, v26
	v_cvt_pk_bf16_f32 v18, v22, v18
	v_mul_f32_e32 v22, v83, v23
	v_add_f32_e32 v23, v22, v22
	v_mul_f32_e32 v23, 0x3fb8aa3b, v23
	v_exp_f32_e32 v23, v23
	v_exp_f32_e32 v19, v19
	v_add_f32_e32 v24, v24, v92
	v_mul_f32_e32 v24, 0xbfb8aa3b, v24
	v_sub_f32_e32 v23, 1.0, v23
	v_exp_f32_e32 v24, v24
	v_max_f32_e32 v23, 0x1e3ce508, v23
	v_add_f32_e32 v19, 1.0, v19
	v_mul_f32_e32 v26, v19, v23
	v_mul_f32_e32 v19, v19, v26
	v_rsq_f32_e32 v19, v19
	v_add_f32_e32 v24, 1.0, v24
	v_rcp_f32_e64 v24, -v24
	v_add_f32_e32 v20, v20, v80
	v_mul_f32_e32 v19, v23, v19
	v_add_f32_e32 v23, v25, v93
	v_mul_f32_e32 v23, 0xbfb8aa3b, v23
	v_mul_f32_e32 v24, v84, v24
	v_exp_f32_e32 v23, v23
	v_add_f32_e32 v26, v24, v24
	v_mul_f32_e32 v26, 0x3fb8aa3b, v26
	v_exp_f32_e32 v26, v26
	v_mul_f32_e32 v20, 0xbfb8aa3b, v20
	v_exp_f32_e32 v20, v20
	v_add_f32_e32 v23, 1.0, v23
	v_and_b32_e32 v27, 0xffff0000, v76
	v_rcp_f32_e64 v23, -v23
	v_mul_f32_e32 v19, v19, v27
	v_cvt_pk_bf16_f32 v19, v22, v19
	v_sub_f32_e32 v22, 1.0, v26
	v_max_f32_e32 v22, 0x1e3ce508, v22
	v_add_f32_e32 v20, 1.0, v20
	v_mul_f32_e32 v25, v20, v22
	v_mul_f32_e32 v23, v85, v23
	v_mul_f32_e32 v20, v20, v25
	v_add_f32_e32 v25, v23, v23
	v_mul_f32_e32 v25, 0x3fb8aa3b, v25
	v_add_f32_e32 v21, v21, v81
	v_exp_f32_e32 v25, v25
	v_mul_f32_e32 v21, 0xbfb8aa3b, v21
	v_exp_f32_e32 v21, v21
	v_rsq_f32_e32 v20, v20
	v_sub_f32_e32 v25, 1.0, v25
	v_max_f32_e32 v25, 0x1e3ce508, v25
	v_add_f32_e32 v21, 1.0, v21
	v_mul_f32_e32 v26, v21, v25
	v_mul_f32_e32 v21, v21, v26
	v_rsq_f32_e32 v21, v21
	v_lshlrev_b32_e32 v28, 16, v77
	v_and_b32_e32 v30, 0xffff0000, v77
	v_mul_f32_e32 v20, v22, v20
	v_mul_f32_e32 v21, v25, v21
	v_mul_f32_e32 v20, v20, v28
	v_mul_f32_e32 v21, v21, v30
	v_cvt_pk_bf16_f32 v20, v24, v20
	v_cvt_pk_bf16_f32 v21, v23, v21
	global_store_dwordx4 v[74:75], v[18:21], off offset:16
	v_add_f32_e32 v14, v14, v90
	v_mul_f32_e32 v14, 0xbfb8aa3b, v14
	v_exp_f32_e32 v14, v14
	v_add_f32_e32 v10, v10, v78
	v_mul_f32_e32 v10, 0xbfb8aa3b, v10
	v_exp_f32_e32 v10, v10
	v_add_f32_e32 v14, 1.0, v14
	v_rcp_f32_e64 v14, -v14
	v_add_f32_e32 v15, v15, v91
	v_mul_f32_e32 v15, 0xbfb8aa3b, v15
	v_add_f32_e32 v10, 1.0, v10
	v_mul_f32_e32 v14, v82, v14
	v_add_f32_e32 v21, v14, v14
	v_mul_f32_e32 v21, 0x3fb8aa3b, v21
	v_exp_f32_e32 v21, v21
	v_exp_f32_e32 v15, v15
	v_lshlrev_b32_e32 v18, 16, v72
	v_add_f32_e32 v11, v11, v79
	v_sub_f32_e32 v21, 1.0, v21
	v_max_f32_e32 v21, 0x1e3ce508, v21
	v_mul_f32_e32 v22, v10, v21
	v_mul_f32_e32 v10, v10, v22
	v_rsq_f32_e32 v10, v10
	v_add_f32_e32 v15, 1.0, v15
	v_rcp_f32_e64 v15, -v15
	v_mul_f32_e32 v11, 0xbfb8aa3b, v11
	v_mul_f32_e32 v10, v21, v10
	v_mul_f32_e32 v10, v10, v18
	v_cvt_pk_bf16_f32 v10, v14, v10
	v_mul_f32_e32 v14, v83, v15
	v_add_f32_e32 v15, v14, v14
	v_mul_f32_e32 v15, 0x3fb8aa3b, v15
	v_exp_f32_e32 v15, v15
	v_exp_f32_e32 v11, v11
	v_add_f32_e32 v16, v16, v92
	v_mul_f32_e32 v16, 0xbfb8aa3b, v16
	v_sub_f32_e32 v15, 1.0, v15
	v_exp_f32_e32 v16, v16
	v_max_f32_e32 v15, 0x1e3ce508, v15
	v_add_f32_e32 v11, 1.0, v11
	v_mul_f32_e32 v18, v11, v15
	v_mul_f32_e32 v11, v11, v18
	v_rsq_f32_e32 v11, v11
	v_add_f32_e32 v16, 1.0, v16
	v_rcp_f32_e64 v16, -v16
	v_add_f32_e32 v12, v12, v80
	v_mul_f32_e32 v11, v15, v11
	v_add_f32_e32 v15, v17, v93
	v_mul_f32_e32 v15, 0xbfb8aa3b, v15
	v_mul_f32_e32 v16, v84, v16
	v_exp_f32_e32 v15, v15
	v_add_f32_e32 v18, v16, v16
	v_mul_f32_e32 v18, 0x3fb8aa3b, v18
	v_exp_f32_e32 v18, v18
	v_mul_f32_e32 v12, 0xbfb8aa3b, v12
	v_exp_f32_e32 v12, v12
	v_add_f32_e32 v15, 1.0, v15
	v_and_b32_e32 v19, 0xffff0000, v72
	v_rcp_f32_e64 v15, -v15
	v_mul_f32_e32 v11, v11, v19
	v_cvt_pk_bf16_f32 v11, v14, v11
	v_sub_f32_e32 v14, 1.0, v18
	v_max_f32_e32 v14, 0x1e3ce508, v14
	v_add_f32_e32 v12, 1.0, v12
	v_mul_f32_e32 v17, v12, v14
	v_mul_f32_e32 v15, v85, v15
	v_mul_f32_e32 v12, v12, v17
	v_add_f32_e32 v17, v15, v15
	v_mul_f32_e32 v17, 0x3fb8aa3b, v17
	v_add_f32_e32 v13, v13, v81
	v_exp_f32_e32 v17, v17
	v_mul_f32_e32 v13, 0xbfb8aa3b, v13
	v_exp_f32_e32 v13, v13
	v_rsq_f32_e32 v12, v12
	v_sub_f32_e32 v17, 1.0, v17
	v_max_f32_e32 v17, 0x1e3ce508, v17
	v_add_f32_e32 v13, 1.0, v13
	v_mul_f32_e32 v18, v13, v17
	v_mul_f32_e32 v13, v13, v18
	v_rsq_f32_e32 v13, v13
	v_lshlrev_b32_e32 v20, 16, v73
	v_and_b32_e32 v22, 0xffff0000, v73
	v_mul_f32_e32 v12, v14, v12
	v_mul_f32_e32 v13, v17, v13
	v_mul_f32_e32 v12, v12, v20
	v_mul_f32_e32 v13, v13, v22
	v_cvt_pk_bf16_f32 v12, v16, v12
	v_cvt_pk_bf16_f32 v13, v15, v13
	global_store_dwordx4 v[70:71], v[10:13], off offset:16
	v_add_f32_e32 v6, v6, v90
	v_mul_f32_e32 v6, 0xbfb8aa3b, v6
	v_exp_f32_e32 v6, v6
	v_add_f32_e32 v2, v2, v78
	v_mul_f32_e32 v2, 0xbfb8aa3b, v2
	v_exp_f32_e32 v2, v2
	v_add_f32_e32 v6, 1.0, v6
	v_rcp_f32_e64 v6, -v6
	v_add_f32_e32 v7, v7, v91
	v_mul_f32_e32 v7, 0xbfb8aa3b, v7
	v_add_f32_e32 v2, 1.0, v2
	v_mul_f32_e32 v6, v82, v6
	v_add_f32_e32 v13, v6, v6
	v_mul_f32_e32 v13, 0x3fb8aa3b, v13
	v_exp_f32_e32 v13, v13
	v_exp_f32_e32 v7, v7
	v_lshlrev_b32_e32 v10, 16, v68
	v_add_f32_e32 v3, v3, v79
	v_sub_f32_e32 v13, 1.0, v13
	v_max_f32_e32 v13, 0x1e3ce508, v13
	v_mul_f32_e32 v14, v2, v13
	v_mul_f32_e32 v2, v2, v14
	v_rsq_f32_e32 v2, v2
	v_add_f32_e32 v7, 1.0, v7
	v_rcp_f32_e64 v7, -v7
	v_mul_f32_e32 v3, 0xbfb8aa3b, v3
	v_mul_f32_e32 v2, v13, v2
	v_mul_f32_e32 v2, v2, v10
	v_cvt_pk_bf16_f32 v2, v6, v2
	v_mul_f32_e32 v6, v83, v7
	v_add_f32_e32 v7, v6, v6
	v_mul_f32_e32 v7, 0x3fb8aa3b, v7
	v_exp_f32_e32 v7, v7
	v_exp_f32_e32 v3, v3
	v_add_f32_e32 v8, v8, v92
	v_mul_f32_e32 v8, 0xbfb8aa3b, v8
	v_sub_f32_e32 v7, 1.0, v7
	v_exp_f32_e32 v8, v8
	v_max_f32_e32 v7, 0x1e3ce508, v7
	v_add_f32_e32 v3, 1.0, v3
	v_mul_f32_e32 v10, v3, v7
	v_mul_f32_e32 v3, v3, v10
	v_rsq_f32_e32 v3, v3
	v_add_f32_e32 v8, 1.0, v8
	v_rcp_f32_e64 v8, -v8
	v_add_f32_e32 v4, v4, v80
	v_mul_f32_e32 v3, v7, v3
	v_add_f32_e32 v7, v9, v93
	v_mul_f32_e32 v7, 0xbfb8aa3b, v7
	v_mul_f32_e32 v8, v84, v8
	v_exp_f32_e32 v7, v7
	v_add_f32_e32 v10, v8, v8
	v_mul_f32_e32 v10, 0x3fb8aa3b, v10
	v_exp_f32_e32 v10, v10
	v_mul_f32_e32 v4, 0xbfb8aa3b, v4
	v_exp_f32_e32 v4, v4
	v_add_f32_e32 v7, 1.0, v7
	v_and_b32_e32 v11, 0xffff0000, v68
	v_rcp_f32_e64 v7, -v7
	v_mul_f32_e32 v3, v3, v11
	v_cvt_pk_bf16_f32 v3, v6, v3
	v_sub_f32_e32 v6, 1.0, v10
	v_max_f32_e32 v6, 0x1e3ce508, v6
	v_add_f32_e32 v4, 1.0, v4
	v_mul_f32_e32 v9, v4, v6
	v_mul_f32_e32 v7, v85, v7
	v_mul_f32_e32 v4, v4, v9
	v_add_f32_e32 v9, v7, v7
	v_mul_f32_e32 v9, 0x3fb8aa3b, v9
	v_add_f32_e32 v5, v5, v81
	v_exp_f32_e32 v9, v9
	v_mul_f32_e32 v5, 0xbfb8aa3b, v5
	v_exp_f32_e32 v5, v5
	v_rsq_f32_e32 v4, v4
	v_sub_f32_e32 v9, 1.0, v9
	v_max_f32_e32 v9, 0x1e3ce508, v9
	v_add_f32_e32 v5, 1.0, v5
	v_mul_f32_e32 v10, v5, v9
	v_mul_f32_e32 v5, v5, v10
	v_rsq_f32_e32 v5, v5
	v_lshlrev_b32_e32 v12, 16, v69
	v_and_b32_e32 v14, 0xffff0000, v69
	v_mul_f32_e32 v4, v6, v4
	v_mul_f32_e32 v5, v9, v5
	v_mul_f32_e32 v4, v4, v12
	v_mul_f32_e32 v5, v5, v14
	v_cvt_pk_bf16_f32 v4, v8, v4
	v_cvt_pk_bf16_f32 v5, v7, v5
	global_store_dwordx4 v[66:67], v[2:5], off offset:16
	s_andn2_b64 vcc, exec, s[40:41]
	s_mov_b64 s[0:1], -1
	s_cbranch_vccnz .LBB0_993
	s_andn2_b64 vcc, exec, s[44:45]
	s_cbranch_vccnz .LBB0_992
	s_barrier
	s_branch .LBB0_992
